# weight conversion rescheduled: phase 0 converts only wt_in; rest of layer-0 weights and layer-1 wt_in converted beside phase 5 (one block of each CU pair converts first, the other last)
# speedup vs baseline: 1.1406x; 1.0013x over previous
.LBB0_21:
	v_readlane_b32 s6, v244, 1
	v_readlane_b32 s7, v244, 2
	s_cmp_lt_u32 s70, 11
	v_readlane_b32 s0, v244, 3
	s_mov_b32 s71, s6
	s_cselect_b64 s[6:7], -1, 0
	s_add_i32 s20, s70, -9
	v_readlane_b32 s1, v244, 4
	v_readlane_b32 s3, v244, 0
	s_cmp_gt_u32 s70, 10
	s_cselect_b64 s[22:23], -1, 0
	s_waitcnt lgkmcnt(0)
	s_load_dwordx2 s[24:25], s[0:1], 0xb8
	s_and_b64 s[18:19], s[22:23], exec
	s_cselect_b32 s18, s20, s70
	s_cmp_lt_u32 s70, 2
	s_cselect_b32 s19, s70, s18
	s_cmp_eq_u32 s70, 5
	s_cbranch_scc0 .Lhk_no
	s_cmpk_lt_u32 s3, 0x100
	s_cbranch_scc1 .Lhk_no
	s_waitcnt lgkmcnt(0)
	s_branch .Lcv_s5y
.Lcvret_disp:
.Lhk_no:
	s_cmp_eq_u32 s19, 0
	s_cbranch_scc1 .Lp0_entry
	s_cmp_eq_u32 s19, 9
	s_cbranch_scc1 .Lgy_entry
	s_cmp_eq_u32 s19, 8
	s_cbranch_scc1 .Lup_entry
	s_cmp_eq_u32 s19, 6
	s_cbranch_scc1 .Lop_entry
	s_cmp_eq_u32 s19, 2
	s_cbranch_scc1 .Lpj_entry
	s_cmp_lt_i32 s19, 5
	s_cbranch_scc1 .LBB0_46
	s_and_b64 s[20:21], s[22:23], exec
	s_cselect_b32 s18, 0x18000, 0
	s_waitcnt lgkmcnt(0)
	s_add_u32 s66, s24, s18
	s_addc_u32 s80, s25, 0
	s_cmp_gt_i32 s19, 7
	s_cbranch_scc0 .LBB0_47
	s_cmp_gt_i32 s19, 8
	s_cbranch_scc0 .LBB0_48
	s_cmp_gt_i32 s19, 9
	s_cbranch_scc0 .LBB0_64
	s_mov_b64 s[20:21], 0
	s_mov_b64 s[24:25], 0
	s_cmp_eq_u32 s19, 10
	v_writelane_b32 v244, s20, 56
	s_nop 1
	v_writelane_b32 v244, s21, 57
	s_cbranch_scc0 .LBB0_65
	s_load_dwordx2 s[30:31], s[0:1], 0x68
	s_and_b64 vcc, exec, s[6:7]
	s_cbranch_vccz .LBB0_334
	s_lshl_b32 s18, s71, 2
	s_abs_i32 s6, s18
	v_cvt_f32_u32_e32 v0, s6
	s_waitcnt vmcnt(0)
	v_mov_b32_e32 v34, v154
	v_mov_b32_e32 v2, v154
	s_sub_i32 s26, 0, s6
	v_rcp_iflag_f32_e32 v0, v0
	s_nop 0
	v_mul_f32_e32 v0, 0x4f7ffffe, v0
	v_cvt_u32_f32_e32 v0, v0
	v_readfirstlane_b32 s7, v2
	s_ashr_i32 s20, s7, 6
	s_add_i32 s7, s18, 0x3fff
	v_readfirstlane_b32 s27, v0
	s_mul_i32 s26, s26, s27
	s_mul_hi_u32 s26, s27, s26
	s_xor_b32 s21, s7, s18
	s_abs_i32 s7, s7
	s_add_i32 s27, s27, s26
	s_mul_hi_u32 s26, s7, s27
	s_mul_i32 s27, s26, s6
	s_sub_i32 s7, s7, s27
	s_ashr_i32 s21, s21, 31
	s_add_i32 s27, s26, 1
	s_sub_i32 s28, s7, s6
	s_cmp_ge_u32 s7, s6
	s_cselect_b32 s26, s27, s26
	s_cselect_b32 s7, s28, s7
	s_add_i32 s27, s26, 1
	s_cmp_ge_u32 s7, s6
	s_cselect_b32 s6, s27, s26
	s_xor_b32 s6, s6, s21
	s_lshl_b32 s52, s3, 2
	s_sub_i32 s7, s6, s21
	s_add_i32 s6, s20, s52
	s_mul_i32 s6, s6, s7
	s_cmpk_gt_i32 s6, 0x3fff
	s_cbranch_scc1 .LBB0_335
	s_load_dwordx2 s[26:27], s[0:1], 0x110
	s_ashr_i32 s20, s6, 12
	s_mulk_i32 s20, 0x1800
	v_lshlrev_b32_e32 v0, 2, v34
	v_and_b32_e32 v35, 0xfc, v0
	s_waitcnt lgkmcnt(0)
	s_cmp_lg_u64 s[26:27], 0
	s_cselect_b64 s[40:41], -1, 0
	s_ashr_i32 s21, s20, 31
	s_lshl_b64 s[34:35], s[20:21], 2
	s_add_u32 s20, s66, s34
	s_addc_u32 s21, s80, s35
	s_add_u32 s36, s20, 0x5000
	s_addc_u32 s37, s21, 0
	s_and_b64 vcc, exec, s[40:41]
	v_lshlrev_b32_e32 v0, 2, v35
	s_cbranch_vccz .LBB0_30
	v_lshl_add_u64 v[10:11], s[36:37], 0, v[0:1]
	v_add_co_u32_e32 v6, vcc, 0x30000, v10
	global_load_dwordx4 v[2:5], v0, s[36:37]
	s_nop 0
	v_addc_co_u32_e32 v7, vcc, 0, v11, vcc
	global_load_dwordx4 v[6:9], v[6:7], off
	s_waitcnt vmcnt(0)
	v_pk_add_f32 v[6:7], v[2:3], v[6:7]
	v_add_co_u32_e32 v2, vcc, 0x60000, v10
	v_pk_add_f32 v[8:9], v[4:5], v[8:9]
	s_nop 0
	v_addc_co_u32_e32 v3, vcc, 0, v11, vcc
	global_load_dwordx4 v[2:5], v[2:3], off
	s_waitcnt vmcnt(0)
	v_pk_add_f32 v[6:7], v[6:7], v[2:3]
	v_add_co_u32_e32 v2, vcc, 0x90000, v10
	v_pk_add_f32 v[8:9], v[8:9], v[4:5]
	s_nop 0
	v_addc_co_u32_e32 v3, vcc, 0, v11, vcc
	global_load_dwordx4 v[2:5], v[2:3], off
	s_waitcnt vmcnt(0)
	v_pk_add_f32 v[68:69], v[8:9], v[4:5]
	v_pk_add_f32 v[66:67], v[6:7], v[2:3]
	global_load_dwordx4 v[2:5], v0, s[30:31]

.LBB0_435:
	s_cmp_eq_u32 s70, 5
	s_cbranch_scc0 .Lbar_go
	v_readlane_b32 s3, v244, 0
	v_readlane_b32 s0, v244, 3
	v_readlane_b32 s1, v244, 4
	s_nop 3
	s_cmpk_lt_u32 s3, 0x100
	s_cbranch_scc0 .Lbar_go
	s_waitcnt vmcnt(0) lgkmcnt(0)
	s_barrier
	s_branch .Lcv_s5o

.Lcv_p0a:
	s_mov_b32 s28, 0
	s_add_i32 s26, s3, 0xffffff40
	s_add_i32 s27, s71, 0xffffff40
	s_mov_b32 s29, 2
	s_movk_i32 s89, 0x780
	s_branch .Lcv_go

.Lcv_p10:
	s_mov_b32 s28, 1
	s_mov_b32 s29, 1
	s_add_i32 s26, s3, 0x1e0
	s_mov_b32 s27, s71
	s_movk_i32 s89, 0x1a00
	s_branch .Lcv_go
.Lcv_s5y:
	s_mov_b32 s28, 0
	s_mov_b32 s29, 5
	s_add_i32 s26, s3, 0xe0
	s_movk_i32 s27, 0x100
	s_movk_i32 s89, 0x10c0
	s_branch .Lcv_go
.Lcv_s5y2:
	s_mov_b32 s28, 1
	s_mov_b32 s29, 3
	s_add_i32 s26, s3, 0xffffff00
	s_movk_i32 s27, 0x100
	s_movk_i32 s89, 0x3c0
	s_branch .Lcv_go
.Lcv_s5o:
	s_mov_b32 s28, 0
	s_mov_b32 s29, 6
	s_add_i32 s26, s3, 0x430
	s_movk_i32 s27, 0x100
	s_movk_i32 s89, 0x1a00
	s_branch .Lcv_go
.Lcv_s5o2:
	s_mov_b32 s28, 1
	s_mov_b32 s29, 4
	s_add_i32 s26, s3, 0xf0
	s_movk_i32 s27, 0x100
	s_movk_i32 s89, 0x780
	s_branch .Lcv_go

.Lcv_done:
	s_cmp_eq_u32 s29, 0
	s_cbranch_scc1 .Lcv_p0b
	s_cmp_eq_u32 s29, 1
	s_cbranch_scc1 .LBB0_518
	s_cmp_eq_u32 s29, 5
	s_cbranch_scc1 .Lcv_s5y2
	s_cmp_eq_u32 s29, 6
	s_cbranch_scc1 .Lcv_s5o2
	s_cmp_eq_u32 s29, 4
	s_cbranch_scc1 .Lbar_go
	s_cmp_eq_u32 s29, 3
	s_cbranch_scc0 .LBB0_435
	s_waitcnt vmcnt(0) lgkmcnt(0)
	s_barrier
	s_branch .Lcvret_disp
	s_branch .LBB0_435
